# P1 epilogue gated-conv tiles: straight-line code with one wave-uniform branch (on v38)
# speedup vs baseline: 1.0047x; 1.0008x over previous
; __device__ __forceinline__ float silu(float v) { return v * sigm(v); }
; __device__ __forceinline__ u32x4 pk8(const f32x4& a, const f32x4& b) { u32x4 w; w.x = pk(a[0], a[1]); w.y = pk(a[2], a[3]); w.z = pk(b[0], b[1]); w.w = pk(b[2], b[3]); return w; }
;     __device__ __forceinline__ void operator()(const f32x4 (&acc)[2][2][4][2], const pg8::Unit& u, int wr, int wc, int fr, int fq) const {
;     ...
;         if (pn < 16) {
;             const bool first = wc < 2; bf16_t* dst = (first ? cu : bz) + pn * 64 + (wc & 1) * 32 + 8 * fq;
; #pragma unroll
;             for (int ai = 0; ai < 2; ++ai)
; #pragma unroll
;                 for (int m = 0; m < 4; ++m) {
;                     f32x4 v0, v1;
; #pragma unroll
;                     for (int j = 0; j < 4; ++j) {
;                         const float a0 = acc[ai][0][m][0][j], a1 = acc[ai][0][m][1][j], b0 = acc[ai][1][m][0][j], b1 = acc[ai][1][m][1][j];
;                         v0[j] = a0 * (first ? b0 : silu(b0)); v1[j] = a1 * (first ? b1 : silu(b1)); }
;                     *(u32x4*)(dst + (size_t)(row0 + ai * 128 + m * 16) * 1024) = pk8(v0, v1);
;                 }
;             return;
.LBB0_672:
	s_lshl_b32 s2, s74, 6
	s_ashr_i32 s3, s2, 31
	v_lshl_add_u64 v[202:203], s[2:3], 1, v[142:143]
	v_lshlrev_b32_e32 v204, 11, v130
	v_mov_b32_e32 v205, 0
	v_lshl_add_u64 v[202:203], v[202:203], 0, v[204:205]
	s_mov_b64 s[98:99], 0x8000
	s_mov_b64 s[100:101], 0x28000
	s_waitcnt lgkmcnt(0)
	s_and_b64 vcc, exec, s[80:81]
	s_cbranch_vccnz .Lepi1_conv_silu
	v_mul_f32_e32 v166, v124, v116
	v_mul_f32_e32 v167, v125, v117
	v_mul_f32_e32 v168, v126, v118
	v_mul_f32_e32 v169, v127, v119
	v_mul_f32_e32 v170, v120, v112
	v_mul_f32_e32 v171, v121, v113
	v_mul_f32_e32 v172, v122, v114
	v_mul_f32_e32 v173, v123, v115
	v_cvt_pk_bf16_f32 v166, v166, v167
	v_cvt_pk_bf16_f32 v167, v168, v169
	v_cvt_pk_bf16_f32 v168, v170, v171
	v_cvt_pk_bf16_f32 v169, v172, v173
	global_store_dwordx4 v[202:203], v[166:169], off
	v_lshl_add_u64 v[202:203], v[202:203], 0, s[98:99]
	v_mul_f32_e32 v174, v108, v100
	v_mul_f32_e32 v175, v109, v101
	v_mul_f32_e32 v176, v110, v102
	v_mul_f32_e32 v177, v111, v103
	v_mul_f32_e32 v178, v104, v96
	v_mul_f32_e32 v179, v105, v97
	v_mul_f32_e32 v180, v106, v98
	v_mul_f32_e32 v181, v107, v99
	v_cvt_pk_bf16_f32 v174, v174, v175
	v_cvt_pk_bf16_f32 v175, v176, v177
	v_cvt_pk_bf16_f32 v176, v178, v179
	v_cvt_pk_bf16_f32 v177, v180, v181
	global_store_dwordx4 v[202:203], v[174:177], off
	v_lshl_add_u64 v[202:203], v[202:203], 0, s[98:99]
	v_mul_f32_e32 v166, v92, v84
	v_mul_f32_e32 v167, v93, v85
	v_mul_f32_e32 v168, v94, v86
	v_mul_f32_e32 v169, v95, v87
	v_mul_f32_e32 v170, v88, v80
	v_mul_f32_e32 v171, v89, v81
	v_mul_f32_e32 v172, v90, v82
	v_mul_f32_e32 v173, v91, v83
	v_cvt_pk_bf16_f32 v166, v166, v167
	v_cvt_pk_bf16_f32 v167, v168, v169
	v_cvt_pk_bf16_f32 v168, v170, v171
	v_cvt_pk_bf16_f32 v169, v172, v173
	global_store_dwordx4 v[202:203], v[166:169], off
	v_lshl_add_u64 v[202:203], v[202:203], 0, s[98:99]
	v_mul_f32_e32 v174, v76, v68
	v_mul_f32_e32 v175, v77, v69
	v_mul_f32_e32 v176, v78, v70
	v_mul_f32_e32 v177, v79, v71
	v_mul_f32_e32 v178, v72, v64
	v_mul_f32_e32 v179, v73, v65
	v_mul_f32_e32 v180, v74, v66
	v_mul_f32_e32 v181, v75, v67
	v_cvt_pk_bf16_f32 v174, v174, v175
	v_cvt_pk_bf16_f32 v175, v176, v177
	v_cvt_pk_bf16_f32 v176, v178, v179
	v_cvt_pk_bf16_f32 v177, v180, v181
	global_store_dwordx4 v[202:203], v[174:177], off
	v_lshl_add_u64 v[202:203], v[202:203], 0, s[100:101]
	v_mul_f32_e32 v166, v60, v52
	v_mul_f32_e32 v167, v61, v53
	v_mul_f32_e32 v168, v62, v54
	v_mul_f32_e32 v169, v63, v55
	v_mul_f32_e32 v170, v56, v48
	v_mul_f32_e32 v171, v57, v49
	v_mul_f32_e32 v172, v58, v50
	v_mul_f32_e32 v173, v59, v51
	v_cvt_pk_bf16_f32 v166, v166, v167
	v_cvt_pk_bf16_f32 v167, v168, v169
	v_cvt_pk_bf16_f32 v168, v170, v171
	v_cvt_pk_bf16_f32 v169, v172, v173
	global_store_dwordx4 v[202:203], v[166:169], off
	v_lshl_add_u64 v[202:203], v[202:203], 0, s[98:99]
	v_mul_f32_e32 v174, v44, v36
	v_mul_f32_e32 v175, v45, v37
	v_mul_f32_e32 v176, v46, v38
	v_mul_f32_e32 v177, v47, v39
	v_mul_f32_e32 v178, v40, v32
	v_mul_f32_e32 v179, v41, v33
	v_mul_f32_e32 v180, v42, v34
	v_mul_f32_e32 v181, v43, v35
	v_cvt_pk_bf16_f32 v174, v174, v175
	v_cvt_pk_bf16_f32 v175, v176, v177
	v_cvt_pk_bf16_f32 v176, v178, v179
	v_cvt_pk_bf16_f32 v177, v180, v181
	global_store_dwordx4 v[202:203], v[174:177], off
	v_lshl_add_u64 v[202:203], v[202:203], 0, s[98:99]
	v_mul_f32_e32 v166, v28, v20
	v_mul_f32_e32 v167, v29, v21
	v_mul_f32_e32 v168, v30, v22
	v_mul_f32_e32 v169, v31, v23
	v_mul_f32_e32 v170, v24, v16
	v_mul_f32_e32 v171, v25, v17
	v_mul_f32_e32 v172, v26, v18
	v_mul_f32_e32 v173, v27, v19
	v_cvt_pk_bf16_f32 v166, v166, v167
	v_cvt_pk_bf16_f32 v167, v168, v169
	v_cvt_pk_bf16_f32 v168, v170, v171
	v_cvt_pk_bf16_f32 v169, v172, v173
	global_store_dwordx4 v[202:203], v[166:169], off
	v_lshl_add_u64 v[202:203], v[202:203], 0, s[98:99]
	v_mul_f32_e32 v174, v12, v4
	v_mul_f32_e32 v175, v13, v5
	v_mul_f32_e32 v176, v14, v6
	v_mul_f32_e32 v177, v15, v7
	v_mul_f32_e32 v178, v8, v0
	v_mul_f32_e32 v179, v9, v1
	v_mul_f32_e32 v180, v10, v2
	v_mul_f32_e32 v181, v11, v3
	v_cvt_pk_bf16_f32 v174, v174, v175
	v_cvt_pk_bf16_f32 v175, v176, v177
	v_cvt_pk_bf16_f32 v176, v178, v179
	v_cvt_pk_bf16_f32 v177, v180, v181
	global_store_dwordx4 v[202:203], v[174:177], off
	s_branch .LBB0_802
; __device__ __forceinline__ u32x4 pk8(const f32x4& a, const f32x4& b) { u32x4 w; w.x = pk(a[0], a[1]); w.y = pk(a[2], a[3]); w.z = pk(b[0], b[1]); w.w = pk(b[2], b[3]); return w; }
; __device__ __forceinline__ float sigm(float v) { return __builtin_amdgcn_rcpf(1.f + __builtin_amdgcn_exp2f(-LOG2E * v)); }
; __device__ __forceinline__ float silu(float v) { return v * sigm(v); }
;     __device__ __forceinline__ void operator()(const f32x4 (&acc)[2][2][4][2], const pg8::Unit& u, int wr, int wc, int fr, int fq) const {
;     ...
;         if (pn < 16) {
;             const bool first = wc < 2; bf16_t* dst = (first ? cu : bz) + pn * 64 + (wc & 1) * 32 + 8 * fq;
; #pragma unroll
;             for (int ai = 0; ai < 2; ++ai)
; #pragma unroll
;                 for (int m = 0; m < 4; ++m) {
;                     f32x4 v0, v1;
; #pragma unroll
;                     for (int j = 0; j < 4; ++j) {
;                         const float a0 = acc[ai][0][m][0][j], a1 = acc[ai][0][m][1][j], b0 = acc[ai][1][m][0][j], b1 = acc[ai][1][m][1][j];
;                         v0[j] = a0 * (first ? b0 : silu(b0)); v1[j] = a1 * (first ? b1 : silu(b1)); }
;                     *(u32x4*)(dst + (size_t)(row0 + ai * 128 + m * 16) * 1024) = pk8(v0, v1);
;                 }
;             return;
.Lepi1_conv_silu:
	v_mul_f32_e32 v166, 0xbfb8aa3b, v116
	v_mul_f32_e32 v167, 0xbfb8aa3b, v117
	v_mul_f32_e32 v168, 0xbfb8aa3b, v118
	v_mul_f32_e32 v169, 0xbfb8aa3b, v119
	v_mul_f32_e32 v170, 0xbfb8aa3b, v112
	v_mul_f32_e32 v171, 0xbfb8aa3b, v113
	v_mul_f32_e32 v172, 0xbfb8aa3b, v114
	v_mul_f32_e32 v173, 0xbfb8aa3b, v115
	v_exp_f32_e32 v166, v166
	v_exp_f32_e32 v167, v167
	v_exp_f32_e32 v168, v168
	v_exp_f32_e32 v169, v169
	v_exp_f32_e32 v170, v170
	v_exp_f32_e32 v171, v171
	v_exp_f32_e32 v172, v172
	v_exp_f32_e32 v173, v173
	v_add_f32_e32 v166, 1.0, v166
	v_add_f32_e32 v167, 1.0, v167
	v_add_f32_e32 v168, 1.0, v168
	v_add_f32_e32 v169, 1.0, v169
	v_add_f32_e32 v170, 1.0, v170
	v_add_f32_e32 v171, 1.0, v171
	v_add_f32_e32 v172, 1.0, v172
	v_add_f32_e32 v173, 1.0, v173
	v_rcp_f32_e32 v166, v166
	v_rcp_f32_e32 v167, v167
	v_rcp_f32_e32 v168, v168
	v_rcp_f32_e32 v169, v169
	v_rcp_f32_e32 v170, v170
	v_rcp_f32_e32 v171, v171
	v_rcp_f32_e32 v172, v172
	v_rcp_f32_e32 v173, v173
	v_mul_f32_e32 v166, v116, v166
	v_mul_f32_e32 v167, v117, v167
	v_mul_f32_e32 v168, v118, v168
	v_mul_f32_e32 v169, v119, v169
	v_mul_f32_e32 v170, v112, v170
	v_mul_f32_e32 v171, v113, v171
	v_mul_f32_e32 v172, v114, v172
	v_mul_f32_e32 v173, v115, v173
	v_mul_f32_e32 v166, v124, v166
	v_mul_f32_e32 v167, v125, v167
	v_mul_f32_e32 v168, v126, v168
	v_mul_f32_e32 v169, v127, v169
	v_mul_f32_e32 v170, v120, v170
	v_mul_f32_e32 v171, v121, v171
	v_mul_f32_e32 v172, v122, v172
	v_mul_f32_e32 v173, v123, v173
	v_cvt_pk_bf16_f32 v166, v166, v167
	v_cvt_pk_bf16_f32 v167, v168, v169
	v_cvt_pk_bf16_f32 v168, v170, v171
	v_cvt_pk_bf16_f32 v169, v172, v173
	global_store_dwordx4 v[202:203], v[166:169], off
	v_lshl_add_u64 v[202:203], v[202:203], 0, s[98:99]
	v_mul_f32_e32 v174, 0xbfb8aa3b, v100
	v_mul_f32_e32 v175, 0xbfb8aa3b, v101
	v_mul_f32_e32 v176, 0xbfb8aa3b, v102
	v_mul_f32_e32 v177, 0xbfb8aa3b, v103
	v_mul_f32_e32 v178, 0xbfb8aa3b, v96
	v_mul_f32_e32 v179, 0xbfb8aa3b, v97
	v_mul_f32_e32 v180, 0xbfb8aa3b, v98
	v_mul_f32_e32 v181, 0xbfb8aa3b, v99
	v_exp_f32_e32 v174, v174
	v_exp_f32_e32 v175, v175
	v_exp_f32_e32 v176, v176
	v_exp_f32_e32 v177, v177
	v_exp_f32_e32 v178, v178
	v_exp_f32_e32 v179, v179
	v_exp_f32_e32 v180, v180
	v_exp_f32_e32 v181, v181
	v_add_f32_e32 v174, 1.0, v174
	v_add_f32_e32 v175, 1.0, v175
	v_add_f32_e32 v176, 1.0, v176
	v_add_f32_e32 v177, 1.0, v177
	v_add_f32_e32 v178, 1.0, v178
	v_add_f32_e32 v179, 1.0, v179
	v_add_f32_e32 v180, 1.0, v180
	v_add_f32_e32 v181, 1.0, v181
	v_rcp_f32_e32 v174, v174
	v_rcp_f32_e32 v175, v175
	v_rcp_f32_e32 v176, v176
	v_rcp_f32_e32 v177, v177
	v_rcp_f32_e32 v178, v178
	v_rcp_f32_e32 v179, v179
	v_rcp_f32_e32 v180, v180
	v_rcp_f32_e32 v181, v181
	v_mul_f32_e32 v174, v100, v174
	v_mul_f32_e32 v175, v101, v175
	v_mul_f32_e32 v176, v102, v176
	v_mul_f32_e32 v177, v103, v177
	v_mul_f32_e32 v178, v96, v178
	v_mul_f32_e32 v179, v97, v179
	v_mul_f32_e32 v180, v98, v180
	v_mul_f32_e32 v181, v99, v181
	v_mul_f32_e32 v174, v108, v174
	v_mul_f32_e32 v175, v109, v175
	v_mul_f32_e32 v176, v110, v176
	v_mul_f32_e32 v177, v111, v177
	v_mul_f32_e32 v178, v104, v178
	v_mul_f32_e32 v179, v105, v179
	v_mul_f32_e32 v180, v106, v180
	v_mul_f32_e32 v181, v107, v181
	v_cvt_pk_bf16_f32 v174, v174, v175
	v_cvt_pk_bf16_f32 v175, v176, v177
	v_cvt_pk_bf16_f32 v176, v178, v179
	v_cvt_pk_bf16_f32 v177, v180, v181
	global_store_dwordx4 v[202:203], v[174:177], off
	v_lshl_add_u64 v[202:203], v[202:203], 0, s[98:99]
	v_mul_f32_e32 v166, 0xbfb8aa3b, v84
	v_mul_f32_e32 v167, 0xbfb8aa3b, v85
	v_mul_f32_e32 v168, 0xbfb8aa3b, v86
	v_mul_f32_e32 v169, 0xbfb8aa3b, v87
	v_mul_f32_e32 v170, 0xbfb8aa3b, v80
	v_mul_f32_e32 v171, 0xbfb8aa3b, v81
	v_mul_f32_e32 v172, 0xbfb8aa3b, v82
	v_mul_f32_e32 v173, 0xbfb8aa3b, v83
	v_exp_f32_e32 v166, v166
	v_exp_f32_e32 v167, v167
	v_exp_f32_e32 v168, v168
	v_exp_f32_e32 v169, v169
	v_exp_f32_e32 v170, v170
	v_exp_f32_e32 v171, v171
	v_exp_f32_e32 v172, v172
	v_exp_f32_e32 v173, v173
	v_add_f32_e32 v166, 1.0, v166
	v_add_f32_e32 v167, 1.0, v167
	v_add_f32_e32 v168, 1.0, v168
	v_add_f32_e32 v169, 1.0, v169
	v_add_f32_e32 v170, 1.0, v170
	v_add_f32_e32 v171, 1.0, v171
	v_add_f32_e32 v172, 1.0, v172
	v_add_f32_e32 v173, 1.0, v173
	v_rcp_f32_e32 v166, v166
	v_rcp_f32_e32 v167, v167
	v_rcp_f32_e32 v168, v168
	v_rcp_f32_e32 v169, v169
	v_rcp_f32_e32 v170, v170
	v_rcp_f32_e32 v171, v171
	v_rcp_f32_e32 v172, v172
	v_rcp_f32_e32 v173, v173
	v_mul_f32_e32 v166, v84, v166
	v_mul_f32_e32 v167, v85, v167
	v_mul_f32_e32 v168, v86, v168
	v_mul_f32_e32 v169, v87, v169
	v_mul_f32_e32 v170, v80, v170
	v_mul_f32_e32 v171, v81, v171
	v_mul_f32_e32 v172, v82, v172
	v_mul_f32_e32 v173, v83, v173
	v_mul_f32_e32 v166, v92, v166
	v_mul_f32_e32 v167, v93, v167
	v_mul_f32_e32 v168, v94, v168
	v_mul_f32_e32 v169, v95, v169
	v_mul_f32_e32 v170, v88, v170
	v_mul_f32_e32 v171, v89, v171
	v_mul_f32_e32 v172, v90, v172
	v_mul_f32_e32 v173, v91, v173
	v_cvt_pk_bf16_f32 v166, v166, v167
	v_cvt_pk_bf16_f32 v167, v168, v169
	v_cvt_pk_bf16_f32 v168, v170, v171
	v_cvt_pk_bf16_f32 v169, v172, v173
	global_store_dwordx4 v[202:203], v[166:169], off
	v_lshl_add_u64 v[202:203], v[202:203], 0, s[98:99]
	v_mul_f32_e32 v174, 0xbfb8aa3b, v68
	v_mul_f32_e32 v175, 0xbfb8aa3b, v69
	v_mul_f32_e32 v176, 0xbfb8aa3b, v70
	v_mul_f32_e32 v177, 0xbfb8aa3b, v71
	v_mul_f32_e32 v178, 0xbfb8aa3b, v64
	v_mul_f32_e32 v179, 0xbfb8aa3b, v65
	v_mul_f32_e32 v180, 0xbfb8aa3b, v66
	v_mul_f32_e32 v181, 0xbfb8aa3b, v67
	v_exp_f32_e32 v174, v174
	v_exp_f32_e32 v175, v175
	v_exp_f32_e32 v176, v176
	v_exp_f32_e32 v177, v177
	v_exp_f32_e32 v178, v178
	v_exp_f32_e32 v179, v179
	v_exp_f32_e32 v180, v180
; __device__ __forceinline__ u32x4 pk8(const f32x4& a, const f32x4& b) { u32x4 w; w.x = pk(a[0], a[1]); w.y = pk(a[2], a[3]); w.z = pk(b[0], b[1]); w.w = pk(b[2], b[3]); return w; }
; __device__ __forceinline__ float sigm(float v) { return __builtin_amdgcn_rcpf(1.f + __builtin_amdgcn_exp2f(-LOG2E * v)); }
; __device__ __forceinline__ float silu(float v) { return v * sigm(v); }
;     __device__ __forceinline__ void operator()(const f32x4 (&acc)[2][2][4][2], const pg8::Unit& u, int wr, int wc, int fr, int fq) const {
;     ...
;         if (pn < 16) {
;             const bool first = wc < 2; bf16_t* dst = (first ? cu : bz) + pn * 64 + (wc & 1) * 32 + 8 * fq;
; #pragma unroll
;             for (int ai = 0; ai < 2; ++ai)
; #pragma unroll
;                 for (int m = 0; m < 4; ++m) {
;                     f32x4 v0, v1;
; #pragma unroll
;                     for (int j = 0; j < 4; ++j) {
;                         const float a0 = acc[ai][0][m][0][j], a1 = acc[ai][0][m][1][j], b0 = acc[ai][1][m][0][j], b1 = acc[ai][1][m][1][j];
;                         v0[j] = a0 * (first ? b0 : silu(b0)); v1[j] = a1 * (first ? b1 : silu(b1)); }
;                     *(u32x4*)(dst + (size_t)(row0 + ai * 128 + m * 16) * 1024) = pk8(v0, v1);
;                 }
;             return;
	v_exp_f32_e32 v181, v181
	v_add_f32_e32 v174, 1.0, v174
	v_add_f32_e32 v175, 1.0, v175
	v_add_f32_e32 v176, 1.0, v176
	v_add_f32_e32 v177, 1.0, v177
	v_add_f32_e32 v178, 1.0, v178
	v_add_f32_e32 v179, 1.0, v179
	v_add_f32_e32 v180, 1.0, v180
	v_add_f32_e32 v181, 1.0, v181
	v_rcp_f32_e32 v174, v174
	v_rcp_f32_e32 v175, v175
	v_rcp_f32_e32 v176, v176
	v_rcp_f32_e32 v177, v177
	v_rcp_f32_e32 v178, v178
	v_rcp_f32_e32 v179, v179
	v_rcp_f32_e32 v180, v180
	v_rcp_f32_e32 v181, v181
	v_mul_f32_e32 v174, v68, v174
	v_mul_f32_e32 v175, v69, v175
	v_mul_f32_e32 v176, v70, v176
	v_mul_f32_e32 v177, v71, v177
	v_mul_f32_e32 v178, v64, v178
	v_mul_f32_e32 v179, v65, v179
	v_mul_f32_e32 v180, v66, v180
	v_mul_f32_e32 v181, v67, v181
	v_mul_f32_e32 v174, v76, v174
	v_mul_f32_e32 v175, v77, v175
	v_mul_f32_e32 v176, v78, v176
	v_mul_f32_e32 v177, v79, v177
	v_mul_f32_e32 v178, v72, v178
	v_mul_f32_e32 v179, v73, v179
	v_mul_f32_e32 v180, v74, v180
	v_mul_f32_e32 v181, v75, v181
	v_cvt_pk_bf16_f32 v174, v174, v175
	v_cvt_pk_bf16_f32 v175, v176, v177
	v_cvt_pk_bf16_f32 v176, v178, v179
	v_cvt_pk_bf16_f32 v177, v180, v181
	global_store_dwordx4 v[202:203], v[174:177], off
	v_lshl_add_u64 v[202:203], v[202:203], 0, s[100:101]
	v_mul_f32_e32 v166, 0xbfb8aa3b, v52
	v_mul_f32_e32 v167, 0xbfb8aa3b, v53
	v_mul_f32_e32 v168, 0xbfb8aa3b, v54
	v_mul_f32_e32 v169, 0xbfb8aa3b, v55
	v_mul_f32_e32 v170, 0xbfb8aa3b, v48
	v_mul_f32_e32 v171, 0xbfb8aa3b, v49
	v_mul_f32_e32 v172, 0xbfb8aa3b, v50
	v_mul_f32_e32 v173, 0xbfb8aa3b, v51
	v_exp_f32_e32 v166, v166
	v_exp_f32_e32 v167, v167
	v_exp_f32_e32 v168, v168
	v_exp_f32_e32 v169, v169
	v_exp_f32_e32 v170, v170
	v_exp_f32_e32 v171, v171
	v_exp_f32_e32 v172, v172
	v_exp_f32_e32 v173, v173
	v_add_f32_e32 v166, 1.0, v166
	v_add_f32_e32 v167, 1.0, v167
	v_add_f32_e32 v168, 1.0, v168
	v_add_f32_e32 v169, 1.0, v169
	v_add_f32_e32 v170, 1.0, v170
	v_add_f32_e32 v171, 1.0, v171
	v_add_f32_e32 v172, 1.0, v172
	v_add_f32_e32 v173, 1.0, v173
	v_rcp_f32_e32 v166, v166
	v_rcp_f32_e32 v167, v167
	v_rcp_f32_e32 v168, v168
	v_rcp_f32_e32 v169, v169
	v_rcp_f32_e32 v170, v170
	v_rcp_f32_e32 v171, v171
	v_rcp_f32_e32 v172, v172
	v_rcp_f32_e32 v173, v173
	v_mul_f32_e32 v166, v52, v166
	v_mul_f32_e32 v167, v53, v167
	v_mul_f32_e32 v168, v54, v168
	v_mul_f32_e32 v169, v55, v169
	v_mul_f32_e32 v170, v48, v170
	v_mul_f32_e32 v171, v49, v171
	v_mul_f32_e32 v172, v50, v172
	v_mul_f32_e32 v173, v51, v173
	v_mul_f32_e32 v166, v60, v166
	v_mul_f32_e32 v167, v61, v167
	v_mul_f32_e32 v168, v62, v168
	v_mul_f32_e32 v169, v63, v169
	v_mul_f32_e32 v170, v56, v170
	v_mul_f32_e32 v171, v57, v171
	v_mul_f32_e32 v172, v58, v172
	v_mul_f32_e32 v173, v59, v173
	v_cvt_pk_bf16_f32 v166, v166, v167
	v_cvt_pk_bf16_f32 v167, v168, v169
	v_cvt_pk_bf16_f32 v168, v170, v171
	v_cvt_pk_bf16_f32 v169, v172, v173
	global_store_dwordx4 v[202:203], v[166:169], off
	v_lshl_add_u64 v[202:203], v[202:203], 0, s[98:99]
	v_mul_f32_e32 v174, 0xbfb8aa3b, v36
	v_mul_f32_e32 v175, 0xbfb8aa3b, v37
	v_mul_f32_e32 v176, 0xbfb8aa3b, v38
	v_mul_f32_e32 v177, 0xbfb8aa3b, v39
	v_mul_f32_e32 v178, 0xbfb8aa3b, v32
	v_mul_f32_e32 v179, 0xbfb8aa3b, v33
	v_mul_f32_e32 v180, 0xbfb8aa3b, v34
	v_mul_f32_e32 v181, 0xbfb8aa3b, v35
	v_exp_f32_e32 v174, v174
	v_exp_f32_e32 v175, v175
	v_exp_f32_e32 v176, v176
	v_exp_f32_e32 v177, v177
	v_exp_f32_e32 v178, v178
	v_exp_f32_e32 v179, v179
	v_exp_f32_e32 v180, v180
	v_exp_f32_e32 v181, v181
	v_add_f32_e32 v174, 1.0, v174
	v_add_f32_e32 v175, 1.0, v175
	v_add_f32_e32 v176, 1.0, v176
	v_add_f32_e32 v177, 1.0, v177
	v_add_f32_e32 v178, 1.0, v178
	v_add_f32_e32 v179, 1.0, v179
	v_add_f32_e32 v180, 1.0, v180
	v_add_f32_e32 v181, 1.0, v181
	v_rcp_f32_e32 v174, v174
	v_rcp_f32_e32 v175, v175
	v_rcp_f32_e32 v176, v176
	v_rcp_f32_e32 v177, v177
	v_rcp_f32_e32 v178, v178
	v_rcp_f32_e32 v179, v179
	v_rcp_f32_e32 v180, v180
	v_rcp_f32_e32 v181, v181
	v_mul_f32_e32 v174, v36, v174
	v_mul_f32_e32 v175, v37, v175
	v_mul_f32_e32 v176, v38, v176
; __device__ __forceinline__ u32x4 pk8(const f32x4& a, const f32x4& b) { u32x4 w; w.x = pk(a[0], a[1]); w.y = pk(a[2], a[3]); w.z = pk(b[0], b[1]); w.w = pk(b[2], b[3]); return w; }
; __device__ __forceinline__ float sigm(float v) { return __builtin_amdgcn_rcpf(1.f + __builtin_amdgcn_exp2f(-LOG2E * v)); }
; __device__ __forceinline__ float silu(float v) { return v * sigm(v); }
;     __device__ __forceinline__ void operator()(const f32x4 (&acc)[2][2][4][2], const pg8::Unit& u, int wr, int wc, int fr, int fq) const {
;     ...
;         if (pn < 16) {
;             const bool first = wc < 2; bf16_t* dst = (first ? cu : bz) + pn * 64 + (wc & 1) * 32 + 8 * fq;
; #pragma unroll
;             for (int ai = 0; ai < 2; ++ai)
; #pragma unroll
;                 for (int m = 0; m < 4; ++m) {
;                     f32x4 v0, v1;
; #pragma unroll
;                     for (int j = 0; j < 4; ++j) {
;                         const float a0 = acc[ai][0][m][0][j], a1 = acc[ai][0][m][1][j], b0 = acc[ai][1][m][0][j], b1 = acc[ai][1][m][1][j];
;                         v0[j] = a0 * (first ? b0 : silu(b0)); v1[j] = a1 * (first ? b1 : silu(b1)); }
;                     *(u32x4*)(dst + (size_t)(row0 + ai * 128 + m * 16) * 1024) = pk8(v0, v1);
;                 }
;             return;
	v_mul_f32_e32 v177, v39, v177
	v_mul_f32_e32 v178, v32, v178
	v_mul_f32_e32 v179, v33, v179
	v_mul_f32_e32 v180, v34, v180
	v_mul_f32_e32 v181, v35, v181
	v_mul_f32_e32 v174, v44, v174
	v_mul_f32_e32 v175, v45, v175
	v_mul_f32_e32 v176, v46, v176
	v_mul_f32_e32 v177, v47, v177
	v_mul_f32_e32 v178, v40, v178
	v_mul_f32_e32 v179, v41, v179
	v_mul_f32_e32 v180, v42, v180
	v_mul_f32_e32 v181, v43, v181
	v_cvt_pk_bf16_f32 v174, v174, v175
	v_cvt_pk_bf16_f32 v175, v176, v177
	v_cvt_pk_bf16_f32 v176, v178, v179
	v_cvt_pk_bf16_f32 v177, v180, v181
	global_store_dwordx4 v[202:203], v[174:177], off
	v_lshl_add_u64 v[202:203], v[202:203], 0, s[98:99]
	v_mul_f32_e32 v166, 0xbfb8aa3b, v20
	v_mul_f32_e32 v167, 0xbfb8aa3b, v21
	v_mul_f32_e32 v168, 0xbfb8aa3b, v22
	v_mul_f32_e32 v169, 0xbfb8aa3b, v23
	v_mul_f32_e32 v170, 0xbfb8aa3b, v16
	v_mul_f32_e32 v171, 0xbfb8aa3b, v17
	v_mul_f32_e32 v172, 0xbfb8aa3b, v18
	v_mul_f32_e32 v173, 0xbfb8aa3b, v19
	v_exp_f32_e32 v166, v166
	v_exp_f32_e32 v167, v167
	v_exp_f32_e32 v168, v168
	v_exp_f32_e32 v169, v169
	v_exp_f32_e32 v170, v170
	v_exp_f32_e32 v171, v171
	v_exp_f32_e32 v172, v172
	v_exp_f32_e32 v173, v173
	v_add_f32_e32 v166, 1.0, v166
	v_add_f32_e32 v167, 1.0, v167
	v_add_f32_e32 v168, 1.0, v168
	v_add_f32_e32 v169, 1.0, v169
	v_add_f32_e32 v170, 1.0, v170
	v_add_f32_e32 v171, 1.0, v171
	v_add_f32_e32 v172, 1.0, v172
	v_add_f32_e32 v173, 1.0, v173
	v_rcp_f32_e32 v166, v166
	v_rcp_f32_e32 v167, v167
	v_rcp_f32_e32 v168, v168
	v_rcp_f32_e32 v169, v169
	v_rcp_f32_e32 v170, v170
	v_rcp_f32_e32 v171, v171
	v_rcp_f32_e32 v172, v172
	v_rcp_f32_e32 v173, v173
	v_mul_f32_e32 v166, v20, v166
	v_mul_f32_e32 v167, v21, v167
	v_mul_f32_e32 v168, v22, v168
	v_mul_f32_e32 v169, v23, v169
	v_mul_f32_e32 v170, v16, v170
	v_mul_f32_e32 v171, v17, v171
	v_mul_f32_e32 v172, v18, v172
	v_mul_f32_e32 v173, v19, v173
	v_mul_f32_e32 v166, v28, v166
	v_mul_f32_e32 v167, v29, v167
	v_mul_f32_e32 v168, v30, v168
	v_mul_f32_e32 v169, v31, v169
	v_mul_f32_e32 v170, v24, v170
	v_mul_f32_e32 v171, v25, v171
	v_mul_f32_e32 v172, v26, v172
	v_mul_f32_e32 v173, v27, v173
	v_cvt_pk_bf16_f32 v166, v166, v167
	v_cvt_pk_bf16_f32 v167, v168, v169
	v_cvt_pk_bf16_f32 v168, v170, v171
	v_cvt_pk_bf16_f32 v169, v172, v173
	global_store_dwordx4 v[202:203], v[166:169], off
	v_lshl_add_u64 v[202:203], v[202:203], 0, s[98:99]
	v_mul_f32_e32 v174, 0xbfb8aa3b, v4
	v_mul_f32_e32 v175, 0xbfb8aa3b, v5
	v_mul_f32_e32 v176, 0xbfb8aa3b, v6
	v_mul_f32_e32 v177, 0xbfb8aa3b, v7
	v_mul_f32_e32 v178, 0xbfb8aa3b, v0
	v_mul_f32_e32 v179, 0xbfb8aa3b, v1
	v_mul_f32_e32 v180, 0xbfb8aa3b, v2
	v_mul_f32_e32 v181, 0xbfb8aa3b, v3
	v_exp_f32_e32 v174, v174
	v_exp_f32_e32 v175, v175
	v_exp_f32_e32 v176, v176
	v_exp_f32_e32 v177, v177
	v_exp_f32_e32 v178, v178
	v_exp_f32_e32 v179, v179
	v_exp_f32_e32 v180, v180
	v_exp_f32_e32 v181, v181
	v_add_f32_e32 v174, 1.0, v174
	v_add_f32_e32 v175, 1.0, v175
	v_add_f32_e32 v176, 1.0, v176
	v_add_f32_e32 v177, 1.0, v177
	v_add_f32_e32 v178, 1.0, v178
	v_add_f32_e32 v179, 1.0, v179
	v_add_f32_e32 v180, 1.0, v180
	v_add_f32_e32 v181, 1.0, v181
	v_rcp_f32_e32 v174, v174
	v_rcp_f32_e32 v175, v175
	v_rcp_f32_e32 v176, v176
	v_rcp_f32_e32 v177, v177
	v_rcp_f32_e32 v178, v178
	v_rcp_f32_e32 v179, v179
	v_rcp_f32_e32 v180, v180
	v_rcp_f32_e32 v181, v181
	v_mul_f32_e32 v174, v4, v174
	v_mul_f32_e32 v175, v5, v175
	v_mul_f32_e32 v176, v6, v176
	v_mul_f32_e32 v177, v7, v177
	v_mul_f32_e32 v178, v0, v178
	v_mul_f32_e32 v179, v1, v179
	v_mul_f32_e32 v180, v2, v180
	v_mul_f32_e32 v181, v3, v181
	v_mul_f32_e32 v174, v12, v174
	v_mul_f32_e32 v175, v13, v175
	v_mul_f32_e32 v176, v14, v176
	v_mul_f32_e32 v177, v15, v177
	v_mul_f32_e32 v178, v8, v178
	v_mul_f32_e32 v179, v9, v179
	v_mul_f32_e32 v180, v10, v180
	v_mul_f32_e32 v181, v11, v181
	v_cvt_pk_bf16_f32 v174, v174, v175
	v_cvt_pk_bf16_f32 v175, v176, v177
	v_cvt_pk_bf16_f32 v176, v178, v179
	v_cvt_pk_bf16_f32 v177, v180, v181
	global_store_dwordx4 v[202:203], v[174:177], off
	s_branch .LBB0_802
